# scan stages A/B: raw-row loads issued together with one wait, LoRA weight loads issued upfront
# speedup vs baseline: 1.0502x; 1.0018x over previous
.LBB0_498:
	s_lshl_b32 s2, s26, 4
	s_or_b32 s34, s2, s24
	s_add_i32 s3, s34, -1
	v_mov_b32_e32 v64, 0
	v_mov_b32_e32 v68, 0
	v_mov_b32_e32 v69, 0
	v_mov_b32_e32 v70, 0
	v_mov_b32_e32 v71, 0
	s_mov_b64 s[36:37], 0
	s_and_saveexec_b64 s[22:23], s[6:7]
	s_cbranch_execz .LBB0_500
	v_add_u32_e32 v65, s3, v220
	v_min_i32_e32 v66, s29, v65
	v_mov_b32_e32 v67, s25
	v_cmp_le_i32_e32 vcc, s25, v65
	s_nop 1
	v_cndmask_b32_e32 v66, v67, v66, vcc
	v_mad_i64_i32 v[66:67], s[16:17], v66, s70, v[192:193]
	global_load_dwordx4 v[68:71], v[66:67], off offset:3072
	v_cmp_gt_i32_e64 s[16:17], s28, v65
	s_and_b64 s[36:37], vcc, s[16:17]
.LBB0_500:
	s_or_b64 exec, exec, s[22:23]
	v_mov_b32_e32 v65, 0
	v_mov_b32_e32 v66, 0
	v_mov_b32_e32 v67, 0
	s_mov_b64 s[98:99], 0
	s_and_saveexec_b64 s[22:23], s[8:9]
	s_cbranch_execz .LBB0_502
	v_add_u32_e32 v72, s3, v221
	v_min_i32_e32 v64, s29, v72
	v_mov_b32_e32 v65, s25
	v_cmp_le_i32_e32 vcc, s25, v72
	s_nop 1
	v_cndmask_b32_e32 v64, v65, v64, vcc
	v_mad_i64_i32 v[64:65], s[16:17], v64, s70, v[194:195]
	global_load_dwordx4 v[64:67], v[64:65], off offset:3072
	v_cmp_gt_i32_e64 s[16:17], s28, v72
	s_and_b64 s[98:99], vcc, s[16:17]
.LBB0_502:
	s_or_b64 exec, exec, s[22:23]
	v_mov_b32_e32 v72, 0
	v_mov_b32_e32 v73, 0
	v_mov_b32_e32 v74, 0
	v_mov_b32_e32 v75, 0
	s_mov_b64 s[100:101], 0
	s_and_saveexec_b64 s[22:23], s[10:11]
	s_cbranch_execz .LBB0_504
	v_add_u32_e32 v76, s3, v222
	v_min_i32_e32 v72, s29, v76
	v_mov_b32_e32 v73, s25
	v_cmp_le_i32_e32 vcc, s25, v76
	s_nop 1
	v_cndmask_b32_e32 v72, v73, v72, vcc
	v_mad_i64_i32 v[72:73], s[16:17], v72, s70, v[198:199]
	global_load_dwordx4 v[72:75], v[72:73], off offset:3072
	v_cmp_gt_i32_e64 s[16:17], s28, v76
	s_and_b64 s[100:101], vcc, s[16:17]
.LBB0_504:
	s_or_b64 exec, exec, s[22:23]
	s_waitcnt vmcnt(0)
	v_cndmask_b32_e64 v68, 0, v68, s[36:37]
	v_cndmask_b32_e64 v69, 0, v69, s[36:37]
	v_cndmask_b32_e64 v70, 0, v70, s[36:37]
	v_cndmask_b32_e64 v71, 0, v71, s[36:37]
	v_cndmask_b32_e64 v64, 0, v64, s[98:99]
	v_cndmask_b32_e64 v65, 0, v65, s[98:99]
	v_cndmask_b32_e64 v66, 0, v66, s[98:99]
	v_cndmask_b32_e64 v67, 0, v67, s[98:99]
	v_cndmask_b32_e64 v72, 0, v72, s[100:101]
	v_cndmask_b32_e64 v73, 0, v73, s[100:101]
	v_cndmask_b32_e64 v74, 0, v74, s[100:101]
	v_cndmask_b32_e64 v75, 0, v75, s[100:101]
	s_waitcnt vmcnt(63) expcnt(7) lgkmcnt(15)
	s_barrier
	s_and_saveexec_b64 s[16:17], s[6:7]
	s_cbranch_execz .LBB0_545
	ds_write_b128 v184, v[68:71] offset:49152
	s_or_b64 exec, exec, s[16:17]
	s_and_saveexec_b64 s[16:17], s[8:9]
	s_cbranch_execnz .LBB0_546

.LBB0_508:
	s_or_b64 exec, exec, s[16:17]
	s_sub_i32 s35, s27, s2
	s_add_i32 s2, s35, -16
	v_mov_b32_e32 v64, 0
	v_mov_b32_e32 v68, 0
	v_mov_b32_e32 v69, 0
	v_mov_b32_e32 v70, 0
	v_mov_b32_e32 v71, 0
	s_mov_b64 s[36:37], 0
	s_and_saveexec_b64 s[22:23], s[6:7]
	s_cbranch_execz .LBB0_510
	v_add_u32_e32 v65, s2, v220
	v_min_i32_e32 v66, s29, v65
	v_mov_b32_e32 v67, s25
	v_cmp_le_i32_e32 vcc, s25, v65
	s_nop 1
	v_cndmask_b32_e32 v66, v67, v66, vcc
	v_mad_i64_i32 v[66:67], s[16:17], v66, s70, v[192:193]
	global_load_dwordx4 v[68:71], v[66:67], off offset:3072
	v_cmp_gt_i32_e64 s[16:17], s28, v65
	s_and_b64 s[36:37], vcc, s[16:17]
.LBB0_510:
	s_or_b64 exec, exec, s[22:23]
	v_mov_b32_e32 v65, 0
	v_mov_b32_e32 v66, 0
	v_mov_b32_e32 v67, 0
	s_mov_b64 s[98:99], 0
	s_and_saveexec_b64 s[22:23], s[8:9]
	s_cbranch_execz .LBB0_512
	v_add_u32_e32 v72, s2, v221
	v_min_i32_e32 v64, s29, v72
	v_mov_b32_e32 v65, s25
	v_cmp_le_i32_e32 vcc, s25, v72
	s_nop 1
	v_cndmask_b32_e32 v64, v65, v64, vcc
	v_mad_i64_i32 v[64:65], s[16:17], v64, s70, v[194:195]
	global_load_dwordx4 v[64:67], v[64:65], off offset:3072
	v_cmp_gt_i32_e64 s[16:17], s28, v72
	s_and_b64 s[98:99], vcc, s[16:17]
.LBB0_512:
	s_or_b64 exec, exec, s[22:23]
	v_mov_b32_e32 v72, 0
	v_mov_b32_e32 v73, 0
	v_mov_b32_e32 v74, 0
	v_mov_b32_e32 v75, 0
	s_mov_b64 s[100:101], 0
	s_and_saveexec_b64 s[22:23], s[10:11]
	s_cbranch_execz .LBB0_514
	v_add_u32_e32 v76, s2, v222
	v_min_i32_e32 v72, s29, v76
	v_mov_b32_e32 v73, s25
	v_cmp_le_i32_e32 vcc, s25, v76
	v_cmp_gt_i32_e64 s[16:17], s28, v76
	s_nop 0
	v_cndmask_b32_e32 v72, v73, v72, vcc
	v_mad_i64_i32 v[72:73], s[2:3], v72, s70, v[198:199]
	global_load_dwordx4 v[72:75], v[72:73], off offset:3072
	s_and_b64 s[100:101], vcc, s[16:17]
.LBB0_514:
	s_or_b64 exec, exec, s[22:23]
	s_waitcnt vmcnt(0)
	v_cndmask_b32_e64 v68, 0, v68, s[36:37]
	v_cndmask_b32_e64 v69, 0, v69, s[36:37]
	v_cndmask_b32_e64 v70, 0, v70, s[36:37]
	v_cndmask_b32_e64 v71, 0, v71, s[36:37]
	v_cndmask_b32_e64 v64, 0, v64, s[98:99]
	v_cndmask_b32_e64 v65, 0, v65, s[98:99]
	v_cndmask_b32_e64 v66, 0, v66, s[98:99]
	v_cndmask_b32_e64 v67, 0, v67, s[98:99]
	v_cndmask_b32_e64 v72, 0, v72, s[100:101]
	v_cndmask_b32_e64 v73, 0, v73, s[100:101]
	v_cndmask_b32_e64 v74, 0, v74, s[100:101]
	v_cndmask_b32_e64 v75, 0, v75, s[100:101]
	s_waitcnt lgkmcnt(0)
	s_barrier
	global_load_dword v82, v[164:165], off
	global_load_dword v83, v[166:167], off
	global_load_dword v84, v[164:165], off offset:2048
	global_load_dword v85, v[168:169], off
	global_load_dword v80, v[170:171], off
	global_load_dword v81, v[172:173], off
	global_load_dword v79, v[176:177], off
	global_load_dword v78, v[178:179], off
	global_load_dword v77, v[180:181], off
	global_load_dword v76, v[182:183], off
	ds_read_u16 v86, v175 offset:49152
	ds_read_u16 v87, v175 offset:49792
	ds_read_u16 v88, v175 offset:50432
	ds_read_u16 v89, v175 offset:55552
	s_waitcnt lgkmcnt(3)
	v_lshlrev_b32_e32 v86, 16, v86
	s_waitcnt lgkmcnt(2)
	v_lshlrev_b32_e32 v87, 16, v87
	v_sub_f32_e32 v86, v86, v87
	s_waitcnt lgkmcnt(1)
	v_lshlrev_b32_e32 v88, 16, v88
	v_sub_f32_e32 v88, v88, v87
	s_waitcnt lgkmcnt(0)
	v_lshlrev_b32_e32 v89, 16, v89
	s_waitcnt vmcnt(9)
	v_fmac_f32_e32 v87, v82, v86
	s_waitcnt vmcnt(8)
	v_fmac_f32_e32 v87, v83, v88
	ds_write_b32 v209, v87
	ds_read_u16 v86, v175 offset:51712
	ds_read_u16 v87, v175 offset:52352
	ds_read_u16 v88, v175 offset:52992
	s_waitcnt lgkmcnt(2)
	v_lshlrev_b32_e32 v86, 16, v86
	s_waitcnt lgkmcnt(1)
	v_lshlrev_b32_e32 v87, 16, v87
	v_sub_f32_e32 v86, v86, v87
	s_waitcnt lgkmcnt(0)
	v_lshlrev_b32_e32 v88, 16, v88
	v_sub_f32_e32 v88, v88, v87
	v_fmac_f32_e32 v87, v82, v86
	v_fmac_f32_e32 v87, v83, v88
	ds_read_u16 v86, v175 offset:54272
	ds_read_u16 v88, v175 offset:54912
	s_waitcnt lgkmcnt(1)
	v_lshlrev_b32_e32 v86, 16, v86
	s_waitcnt lgkmcnt(0)
	v_lshlrev_b32_e32 v88, 16, v88
	v_sub_f32_e32 v86, v86, v88
	v_sub_f32_e32 v89, v89, v88
	v_fmac_f32_e32 v88, v82, v86
	v_fmac_f32_e32 v88, v83, v89
	ds_write2st64_b32 v210, v87, v88 offset0:4 offset1:8
	ds_read_u16 v86, v175 offset:56832
	ds_read_u16 v87, v175 offset:57472
	ds_read_u16 v88, v175 offset:58112
	s_waitcnt lgkmcnt(2)
	v_lshlrev_b32_e32 v86, 16, v86
	s_waitcnt lgkmcnt(1)
	v_lshlrev_b32_e32 v87, 16, v87
	v_sub_f32_e32 v86, v86, v87
	s_waitcnt lgkmcnt(0)
	v_lshlrev_b32_e32 v88, 16, v88
	v_sub_f32_e32 v88, v88, v87
	v_fmac_f32_e32 v87, v82, v86
	v_fmac_f32_e32 v87, v83, v88
	ds_read_u16 v82, v175 offset:49280
	ds_read_u16 v83, v175 offset:49920
	ds_read_u16 v86, v175 offset:50560
	s_waitcnt lgkmcnt(2)
	v_lshlrev_b32_e32 v82, 16, v82
	s_waitcnt lgkmcnt(1)
	v_lshlrev_b32_e32 v83, 16, v83
	v_sub_f32_e32 v82, v82, v83
	s_waitcnt lgkmcnt(0)
	v_lshlrev_b32_e32 v86, 16, v86
	v_sub_f32_e32 v86, v86, v83
	s_waitcnt vmcnt(7)
	v_fmac_f32_e32 v83, v84, v82
	s_waitcnt vmcnt(6)
	v_fmac_f32_e32 v83, v85, v86
	ds_write2st64_b32 v210, v87, v83 offset0:12 offset1:16
	ds_read_u16 v82, v175 offset:51840
	ds_read_u16 v83, v175 offset:52480
	ds_read_u16 v86, v175 offset:53120
	ds_read_u16 v87, v175 offset:55680
	s_waitcnt lgkmcnt(3)
	v_lshlrev_b32_e32 v82, 16, v82
	s_waitcnt lgkmcnt(2)
	v_lshlrev_b32_e32 v83, 16, v83
	v_sub_f32_e32 v82, v82, v83
	s_waitcnt lgkmcnt(1)
	v_lshlrev_b32_e32 v86, 16, v86
	v_sub_f32_e32 v86, v86, v83
	v_fmac_f32_e32 v83, v84, v82
	v_fmac_f32_e32 v83, v85, v86
	ds_read_u16 v82, v175 offset:54400
	ds_read_u16 v86, v175 offset:55040
	s_waitcnt lgkmcnt(2)
	v_lshlrev_b32_e32 v87, 16, v87
	s_waitcnt lgkmcnt(1)
	v_lshlrev_b32_e32 v82, 16, v82
	s_waitcnt lgkmcnt(0)
	v_lshlrev_b32_e32 v86, 16, v86
	v_sub_f32_e32 v82, v82, v86
	v_sub_f32_e32 v87, v87, v86
	v_fmac_f32_e32 v86, v84, v82
	v_fmac_f32_e32 v86, v85, v87
	ds_write2st64_b32 v211, v83, v86 offset0:4 offset1:8
	ds_read_u16 v82, v175 offset:56960
	ds_read_u16 v83, v175 offset:57600
	ds_read_u16 v86, v175 offset:58240
	s_waitcnt lgkmcnt(2)
	v_lshlrev_b32_e32 v82, 16, v82
	s_waitcnt lgkmcnt(1)
	v_lshlrev_b32_e32 v83, 16, v83
	v_sub_f32_e32 v82, v82, v83
	s_waitcnt lgkmcnt(0)
	v_lshlrev_b32_e32 v86, 16, v86
	v_sub_f32_e32 v86, v86, v83
	v_fmac_f32_e32 v83, v84, v82
	v_fmac_f32_e32 v83, v85, v86
	ds_write_b32 v211, v83 offset:3072
	ds_read_u16 v82, v175 offset:49408
	ds_read_u16 v83, v175 offset:50048
	ds_read_u16 v84, v175 offset:50688
	ds_read_u16 v85, v175 offset:53248
	s_waitcnt lgkmcnt(3)
	v_lshlrev_b32_e32 v82, 16, v82
	s_waitcnt lgkmcnt(2)
	v_lshlrev_b32_e32 v83, 16, v83
	v_sub_f32_e32 v82, v82, v83
	s_waitcnt lgkmcnt(1)
	v_lshlrev_b32_e32 v84, 16, v84
	v_sub_f32_e32 v84, v84, v83
	s_waitcnt vmcnt(5)
	v_fmac_f32_e32 v83, v80, v82
	s_waitcnt vmcnt(4)
	v_fmac_f32_e32 v83, v81, v84
	ds_read_u16 v82, v175 offset:51968
	ds_read_u16 v84, v175 offset:52608
	s_waitcnt lgkmcnt(2)
	v_lshlrev_b32_e32 v85, 16, v85
	s_waitcnt lgkmcnt(1)
	v_lshlrev_b32_e32 v82, 16, v82
	s_waitcnt lgkmcnt(0)
	v_lshlrev_b32_e32 v84, 16, v84
	v_sub_f32_e32 v82, v82, v84
	v_sub_f32_e32 v85, v85, v84
	v_fmac_f32_e32 v84, v80, v82
	v_fmac_f32_e32 v84, v81, v85
	ds_write2st64_b32 v212, v83, v84 offset0:32 offset1:36
	ds_read_u16 v82, v175 offset:54528
	ds_read_u16 v83, v175 offset:55168
	ds_read_u16 v84, v175 offset:55808
	ds_read_u16 v85, v175 offset:58368
	s_waitcnt lgkmcnt(3)
	v_lshlrev_b32_e32 v82, 16, v82
	s_waitcnt lgkmcnt(2)
	v_lshlrev_b32_e32 v83, 16, v83
	v_sub_f32_e32 v82, v82, v83
	s_waitcnt lgkmcnt(1)
	v_lshlrev_b32_e32 v84, 16, v84
	v_sub_f32_e32 v84, v84, v83
	v_fmac_f32_e32 v83, v80, v82
	v_fmac_f32_e32 v83, v81, v84
	ds_read_u16 v82, v175 offset:57088
	ds_read_u16 v84, v175 offset:57728
	s_waitcnt lgkmcnt(2)
	v_lshlrev_b32_e32 v85, 16, v85
	s_waitcnt lgkmcnt(1)
	v_lshlrev_b32_e32 v82, 16, v82
	s_waitcnt lgkmcnt(0)
	v_lshlrev_b32_e32 v84, 16, v84
	v_sub_f32_e32 v82, v82, v84
	v_sub_f32_e32 v85, v85, v84
	v_fmac_f32_e32 v84, v80, v82
	v_fmac_f32_e32 v84, v81, v85
	ds_read_u16 v80, v175 offset:49536
	ds_read_u16 v81, v175 offset:50176
	ds_read_u16 v82, v175 offset:50816
	ds_write2st64_b32 v212, v83, v84 offset0:40 offset1:44
	s_waitcnt lgkmcnt(3)
	v_lshlrev_b32_e32 v80, 16, v80
	s_waitcnt lgkmcnt(2)
	v_lshlrev_b32_e32 v81, 16, v81
	v_sub_f32_e32 v80, v80, v81
	s_waitcnt lgkmcnt(1)
	v_lshlrev_b32_e32 v82, 16, v82
	v_sub_f32_e32 v82, v82, v81
	s_waitcnt vmcnt(3)
	v_fmac_f32_e32 v81, v79, v80
	s_waitcnt vmcnt(2)
	v_fmac_f32_e32 v81, v78, v82
	v_add_f32_e32 v80, v81, v81
	v_mul_f32_e32 v80, 0x3fb8aa3b, v80
	v_exp_f32_e32 v80, v80
	s_nop 0
	v_add_f32_e32 v80, 1.0, v80
	v_rcp_f32_e32 v80, v80
	s_nop 0
	v_fma_f32 v80, v80, -2.0, 1.0
	v_cvt_pk_bf16_f32 v80, v80, s0
	ds_write_b16 v213, v80 offset:20480
	ds_read_u16 v80, v175 offset:52096
	ds_read_u16 v81, v175 offset:52736
	ds_read_u16 v82, v175 offset:53376
	s_waitcnt lgkmcnt(2)
	v_lshlrev_b32_e32 v80, 16, v80
	s_waitcnt lgkmcnt(1)
	v_lshlrev_b32_e32 v81, 16, v81
	v_sub_f32_e32 v80, v80, v81
	s_waitcnt lgkmcnt(0)
	v_lshlrev_b32_e32 v82, 16, v82
	v_sub_f32_e32 v82, v82, v81
	v_fmac_f32_e32 v81, v79, v80
	v_fmac_f32_e32 v81, v78, v82
	v_add_f32_e32 v80, v81, v81
	v_mul_f32_e32 v80, 0x3fb8aa3b, v80
	v_exp_f32_e32 v80, v80
	s_nop 0
	v_add_f32_e32 v80, 1.0, v80
	v_rcp_f32_e32 v80, v80
	s_nop 0
	v_fma_f32 v80, v80, -2.0, 1.0
	v_cvt_pk_bf16_f32 v80, v80, s0
	ds_write_b16 v214, v80 offset:20992
	ds_read_u16 v80, v175 offset:54656
	ds_read_u16 v81, v175 offset:55296
	ds_read_u16 v82, v175 offset:55936
	s_waitcnt lgkmcnt(2)
	v_lshlrev_b32_e32 v80, 16, v80
	s_waitcnt lgkmcnt(1)
	v_lshlrev_b32_e32 v81, 16, v81
	v_sub_f32_e32 v80, v80, v81
	s_waitcnt lgkmcnt(0)
	v_lshlrev_b32_e32 v82, 16, v82
	v_sub_f32_e32 v82, v82, v81
	v_fmac_f32_e32 v81, v79, v80
	v_fmac_f32_e32 v81, v78, v82
	v_add_f32_e32 v80, v81, v81
	v_mul_f32_e32 v80, 0x3fb8aa3b, v80
	v_exp_f32_e32 v80, v80
	s_nop 0
	v_add_f32_e32 v80, 1.0, v80
	v_rcp_f32_e32 v80, v80
	s_nop 0
	v_fma_f32 v80, v80, -2.0, 1.0
	v_cvt_pk_bf16_f32 v80, v80, s0
	ds_write_b16 v214, v80 offset:21504
	ds_read_u16 v80, v175 offset:57216
	ds_read_u16 v81, v175 offset:57856
	ds_read_u16 v82, v175 offset:58496
	s_waitcnt lgkmcnt(2)
	v_lshlrev_b32_e32 v80, 16, v80
	s_waitcnt lgkmcnt(1)
	v_lshlrev_b32_e32 v81, 16, v81
	v_sub_f32_e32 v80, v80, v81
	s_waitcnt lgkmcnt(0)
	v_lshlrev_b32_e32 v82, 16, v82
	v_sub_f32_e32 v82, v82, v81
	v_fmac_f32_e32 v81, v79, v80
	v_fmac_f32_e32 v81, v78, v82
	v_add_f32_e32 v78, v81, v81
	v_mul_f32_e32 v78, 0x3fb8aa3b, v78
	v_exp_f32_e32 v78, v78
	s_nop 0
	v_add_f32_e32 v78, 1.0, v78
	v_rcp_f32_e32 v78, v78
	s_nop 0
	v_fma_f32 v78, v78, -2.0, 1.0
	v_cvt_pk_bf16_f32 v78, v78, s0
	ds_write_b16 v214, v78 offset:22016
	ds_read_u16 v78, v175 offset:49664
	ds_read_u16 v79, v175 offset:50304
	ds_read_u16 v80, v175 offset:50944
	s_waitcnt lgkmcnt(2)
	v_lshlrev_b32_e32 v78, 16, v78
	s_waitcnt lgkmcnt(1)
	v_lshlrev_b32_e32 v79, 16, v79
	v_sub_f32_e32 v78, v78, v79
	s_waitcnt lgkmcnt(0)
	v_lshlrev_b32_e32 v80, 16, v80
	v_sub_f32_e32 v80, v80, v79
	s_waitcnt vmcnt(1)
	v_fmac_f32_e32 v79, v77, v78
	s_waitcnt vmcnt(0)
	v_fmac_f32_e32 v79, v76, v80
	v_cvt_pk_bf16_f32 v78, v79, s0
	ds_write_b16 v214, v78 offset:22528
	ds_read_u16 v78, v175 offset:52224
	ds_read_u16 v79, v175 offset:52864
	ds_read_u16 v80, v175 offset:53504
	s_waitcnt lgkmcnt(2)
	v_lshlrev_b32_e32 v78, 16, v78
	s_waitcnt lgkmcnt(1)
	v_lshlrev_b32_e32 v79, 16, v79
	v_sub_f32_e32 v78, v78, v79
	s_waitcnt lgkmcnt(0)
	v_lshlrev_b32_e32 v80, 16, v80
	v_sub_f32_e32 v80, v80, v79
	v_fmac_f32_e32 v79, v77, v78
	v_fmac_f32_e32 v79, v76, v80
	v_cvt_pk_bf16_f32 v78, v79, s0
	ds_write_b16 v215, v78 offset:20992
	ds_read_u16 v78, v175 offset:54784
	ds_read_u16 v79, v175 offset:55424
	ds_read_u16 v80, v175 offset:56064
	s_waitcnt lgkmcnt(2)
	v_lshlrev_b32_e32 v78, 16, v78
	s_waitcnt lgkmcnt(1)
	v_lshlrev_b32_e32 v79, 16, v79
	v_sub_f32_e32 v78, v78, v79
	s_waitcnt lgkmcnt(0)
	v_lshlrev_b32_e32 v80, 16, v80
	v_sub_f32_e32 v80, v80, v79
	v_fmac_f32_e32 v79, v77, v78
	v_fmac_f32_e32 v79, v76, v80
	v_cvt_pk_bf16_f32 v78, v79, s0
	ds_write_b16 v215, v78 offset:21504
	ds_read_u16 v78, v175 offset:57344
	ds_read_u16 v79, v175 offset:57984
	ds_read_u16 v80, v175 offset:58624
	s_waitcnt lgkmcnt(2)
	v_lshlrev_b32_e32 v78, 16, v78
	s_waitcnt lgkmcnt(1)
	v_lshlrev_b32_e32 v79, 16, v79
	v_sub_f32_e32 v78, v78, v79
	s_waitcnt lgkmcnt(0)
	v_lshlrev_b32_e32 v80, 16, v80
	v_sub_f32_e32 v80, v80, v79
	v_fmac_f32_e32 v79, v77, v78
	v_fmac_f32_e32 v79, v76, v80
	v_cvt_pk_bf16_f32 v76, v79, s0
	ds_write_b16 v215, v76 offset:22016
	s_waitcnt lgkmcnt(0)
	s_barrier
	s_and_saveexec_b64 s[16:17], s[6:7]
	s_cbranch_execz .LBB0_547
	ds_write_b128 v184, v[68:71] offset:49152
	s_or_b64 exec, exec, s[16:17]
	s_and_saveexec_b64 s[16:17], s[8:9]
	s_cbranch_execnz .LBB0_548

.LBB0_518:
	s_or_b64 exec, exec, s[16:17]
	s_waitcnt lgkmcnt(0)
	s_barrier
	global_load_dword v70, v[164:165], off
	global_load_dword v71, v[166:167], off
	global_load_dword v72, v[164:165], off offset:2048
	global_load_dword v73, v[168:169], off
	global_load_dword v68, v[170:171], off
	global_load_dword v69, v[172:173], off
	global_load_dword v67, v[176:177], off
	global_load_dword v66, v[178:179], off
	global_load_dword v65, v[180:181], off
	global_load_dword v64, v[182:183], off
	ds_read_u16 v74, v216 offset:48512
	ds_read_u16 v75, v216 offset:49152
	ds_read_u16 v76, v216 offset:49792
	ds_read_u16 v77, v217 offset:49792
	s_waitcnt lgkmcnt(3)
	v_lshlrev_b32_e32 v74, 16, v74
	s_waitcnt lgkmcnt(2)
	v_lshlrev_b32_e32 v75, 16, v75
	v_sub_f32_e32 v74, v74, v75
	s_waitcnt lgkmcnt(1)
	v_lshlrev_b32_e32 v76, 16, v76
	v_sub_f32_e32 v76, v76, v75
	s_waitcnt lgkmcnt(0)
	v_lshlrev_b32_e32 v77, 16, v77
	s_waitcnt vmcnt(9)
	v_fmac_f32_e32 v75, v70, v74
	s_waitcnt vmcnt(8)
	v_fmac_f32_e32 v75, v71, v76
	ds_read_u16 v74, v217 offset:48512
	ds_read_u16 v76, v217 offset:49152
	s_waitcnt lgkmcnt(1)
	v_lshlrev_b32_e32 v74, 16, v74
	s_waitcnt lgkmcnt(0)
	v_lshlrev_b32_e32 v76, 16, v76
	v_sub_f32_e32 v74, v74, v76
	v_sub_f32_e32 v77, v77, v76
	v_fmac_f32_e32 v76, v70, v74
	v_fmac_f32_e32 v76, v71, v77
	ds_write2st64_b32 v212, v75, v76 offset0:96 offset1:100
	ds_read_u16 v74, v218 offset:48512
	ds_read_u16 v75, v218 offset:49152
	ds_read_u16 v76, v218 offset:49792
	ds_read_u16 v77, v219 offset:49792
	s_waitcnt lgkmcnt(3)
	v_lshlrev_b32_e32 v74, 16, v74
	s_waitcnt lgkmcnt(2)
	v_lshlrev_b32_e32 v75, 16, v75
	v_sub_f32_e32 v74, v74, v75
	s_waitcnt lgkmcnt(1)
	v_lshlrev_b32_e32 v76, 16, v76
	v_sub_f32_e32 v76, v76, v75
	v_fmac_f32_e32 v75, v70, v74
	v_fmac_f32_e32 v75, v71, v76
	ds_read_u16 v74, v219 offset:48512
	ds_read_u16 v76, v219 offset:49152
	s_waitcnt lgkmcnt(2)
	v_lshlrev_b32_e32 v77, 16, v77
	s_waitcnt lgkmcnt(1)
	v_lshlrev_b32_e32 v74, 16, v74
	s_waitcnt lgkmcnt(0)
	v_lshlrev_b32_e32 v76, 16, v76
	v_sub_f32_e32 v74, v74, v76
	v_sub_f32_e32 v77, v77, v76
	v_fmac_f32_e32 v76, v70, v74
	v_fmac_f32_e32 v76, v71, v77
	ds_read_u16 v70, v216 offset:48640
	ds_read_u16 v71, v216 offset:49280
	ds_read_u16 v74, v216 offset:49920
	ds_write2st64_b32 v212, v75, v76 offset0:104 offset1:108
	ds_read_u16 v75, v217 offset:49920
	s_waitcnt lgkmcnt(4)
	v_lshlrev_b32_e32 v70, 16, v70
	s_waitcnt lgkmcnt(3)
	v_lshlrev_b32_e32 v71, 16, v71
	v_sub_f32_e32 v70, v70, v71
	s_waitcnt lgkmcnt(2)
	v_lshlrev_b32_e32 v74, 16, v74
	v_sub_f32_e32 v74, v74, v71
	s_waitcnt vmcnt(7)
	v_fmac_f32_e32 v71, v72, v70
	s_waitcnt vmcnt(6)
	v_fmac_f32_e32 v71, v73, v74
	ds_read_u16 v70, v217 offset:48640
	ds_read_u16 v74, v217 offset:49280
	s_waitcnt lgkmcnt(2)
	v_lshlrev_b32_e32 v75, 16, v75
	s_waitcnt lgkmcnt(1)
	v_lshlrev_b32_e32 v70, 16, v70
	s_waitcnt lgkmcnt(0)
	v_lshlrev_b32_e32 v74, 16, v74
	v_sub_f32_e32 v70, v70, v74
	v_sub_f32_e32 v75, v75, v74
	v_fmac_f32_e32 v74, v72, v70
	v_fmac_f32_e32 v74, v73, v75
	ds_write2st64_b32 v212, v71, v74 offset0:112 offset1:116
	ds_read_u16 v70, v218 offset:48640
	ds_read_u16 v71, v218 offset:49280
	ds_read_u16 v74, v218 offset:49920
	ds_read_u16 v75, v219 offset:49920
	s_waitcnt lgkmcnt(3)
	v_lshlrev_b32_e32 v70, 16, v70
	s_waitcnt lgkmcnt(2)
	v_lshlrev_b32_e32 v71, 16, v71
	v_sub_f32_e32 v70, v70, v71
	s_waitcnt lgkmcnt(1)
	v_lshlrev_b32_e32 v74, 16, v74
	v_sub_f32_e32 v74, v74, v71
	v_fmac_f32_e32 v71, v72, v70
	v_fmac_f32_e32 v71, v73, v74
	ds_read_u16 v70, v219 offset:48640
	ds_read_u16 v74, v219 offset:49280
	s_waitcnt lgkmcnt(2)
	v_lshlrev_b32_e32 v75, 16, v75
	s_waitcnt lgkmcnt(1)
	v_lshlrev_b32_e32 v70, 16, v70
	s_waitcnt lgkmcnt(0)
	v_lshlrev_b32_e32 v74, 16, v74
	v_sub_f32_e32 v70, v70, v74
	v_sub_f32_e32 v75, v75, v74
	v_fmac_f32_e32 v74, v72, v70
	v_fmac_f32_e32 v74, v73, v75
	ds_write2st64_b32 v212, v71, v74 offset0:120 offset1:124
	ds_read_u16 v70, v216 offset:48768
	ds_read_u16 v71, v216 offset:49408
	ds_read_u16 v72, v216 offset:50048
	ds_read_u16 v73, v217 offset:50048
	s_waitcnt lgkmcnt(3)
	v_lshlrev_b32_e32 v70, 16, v70
	s_waitcnt lgkmcnt(2)
	v_lshlrev_b32_e32 v71, 16, v71
	v_sub_f32_e32 v70, v70, v71
	s_waitcnt lgkmcnt(1)
	v_lshlrev_b32_e32 v72, 16, v72
	v_sub_f32_e32 v72, v72, v71
	s_waitcnt vmcnt(5)
	v_fmac_f32_e32 v71, v68, v70
	s_waitcnt vmcnt(4)
	v_fmac_f32_e32 v71, v69, v72
	ds_read_u16 v70, v217 offset:48768
	ds_read_u16 v72, v217 offset:49408
	s_waitcnt lgkmcnt(2)
	v_lshlrev_b32_e32 v73, 16, v73
	s_waitcnt lgkmcnt(1)
	v_lshlrev_b32_e32 v70, 16, v70
	s_waitcnt lgkmcnt(0)
	v_lshlrev_b32_e32 v72, 16, v72
	v_sub_f32_e32 v70, v70, v72
	v_sub_f32_e32 v73, v73, v72
	v_fmac_f32_e32 v72, v68, v70
	v_fmac_f32_e32 v72, v69, v73
	ds_write2st64_b32 v212, v71, v72 offset0:128 offset1:132
	ds_read_u16 v70, v218 offset:48768
	ds_read_u16 v71, v218 offset:49408
	ds_read_u16 v72, v218 offset:50048
	ds_read_u16 v73, v219 offset:50048
	s_waitcnt lgkmcnt(3)
	v_lshlrev_b32_e32 v70, 16, v70
	s_waitcnt lgkmcnt(2)
	v_lshlrev_b32_e32 v71, 16, v71
	v_sub_f32_e32 v70, v70, v71
	s_waitcnt lgkmcnt(1)
	v_lshlrev_b32_e32 v72, 16, v72
	v_sub_f32_e32 v72, v72, v71
	v_fmac_f32_e32 v71, v68, v70
	v_fmac_f32_e32 v71, v69, v72
	ds_read_u16 v70, v219 offset:48768
	ds_read_u16 v72, v219 offset:49408
	s_waitcnt lgkmcnt(2)
	v_lshlrev_b32_e32 v73, 16, v73
	s_waitcnt lgkmcnt(1)
	v_lshlrev_b32_e32 v70, 16, v70
	s_waitcnt lgkmcnt(0)
	v_lshlrev_b32_e32 v72, 16, v72
	v_sub_f32_e32 v70, v70, v72
	v_sub_f32_e32 v73, v73, v72
	v_fmac_f32_e32 v72, v68, v70
	v_fmac_f32_e32 v72, v69, v73
	ds_read_u16 v68, v216 offset:48896
	ds_read_u16 v69, v216 offset:49536
	ds_read_u16 v70, v216 offset:50176
	ds_write2st64_b32 v212, v71, v72 offset0:136 offset1:140
	s_waitcnt lgkmcnt(3)
	v_lshlrev_b32_e32 v68, 16, v68
	s_waitcnt lgkmcnt(2)
	v_lshlrev_b32_e32 v69, 16, v69
	v_sub_f32_e32 v68, v68, v69
	s_waitcnt lgkmcnt(1)
	v_lshlrev_b32_e32 v70, 16, v70
	v_sub_f32_e32 v70, v70, v69
	s_waitcnt vmcnt(3)
	v_fmac_f32_e32 v69, v67, v68
	s_waitcnt vmcnt(2)
	v_fmac_f32_e32 v69, v66, v70
	v_add_f32_e32 v68, v69, v69
	v_mul_f32_e32 v68, 0x3fb8aa3b, v68
	v_exp_f32_e32 v68, v68
	s_nop 0
	v_add_f32_e32 v68, 1.0, v68
	v_rcp_f32_e32 v68, v68
	s_nop 0
	v_fma_f32 v68, v68, -2.0, 1.0
	v_cvt_pk_bf16_f32 v68, v68, s0
	ds_write_b16 v213, v68 offset:45056
	ds_read_u16 v68, v217 offset:48896
	ds_read_u16 v69, v217 offset:49536
	ds_read_u16 v70, v217 offset:50176
	s_waitcnt lgkmcnt(2)
	v_lshlrev_b32_e32 v68, 16, v68
	s_waitcnt lgkmcnt(1)
	v_lshlrev_b32_e32 v69, 16, v69
	v_sub_f32_e32 v68, v68, v69
	s_waitcnt lgkmcnt(0)
	v_lshlrev_b32_e32 v70, 16, v70
	v_sub_f32_e32 v70, v70, v69
	v_fmac_f32_e32 v69, v67, v68
	v_fmac_f32_e32 v69, v66, v70
	v_add_f32_e32 v68, v69, v69
	v_mul_f32_e32 v68, 0x3fb8aa3b, v68
	v_exp_f32_e32 v68, v68
	s_nop 0
	v_add_f32_e32 v68, 1.0, v68
	v_rcp_f32_e32 v68, v68
	s_nop 0
	v_fma_f32 v68, v68, -2.0, 1.0
	v_cvt_pk_bf16_f32 v68, v68, s0
	ds_write_b16 v214, v68 offset:45568
	ds_read_u16 v68, v218 offset:48896
	ds_read_u16 v69, v218 offset:49536
	ds_read_u16 v70, v218 offset:50176
	s_waitcnt lgkmcnt(2)
	v_lshlrev_b32_e32 v68, 16, v68
	s_waitcnt lgkmcnt(1)
	v_lshlrev_b32_e32 v69, 16, v69
	v_sub_f32_e32 v68, v68, v69
	s_waitcnt lgkmcnt(0)
	v_lshlrev_b32_e32 v70, 16, v70
	v_sub_f32_e32 v70, v70, v69
	v_fmac_f32_e32 v69, v67, v68
	v_fmac_f32_e32 v69, v66, v70
	v_add_f32_e32 v68, v69, v69
	v_mul_f32_e32 v68, 0x3fb8aa3b, v68
	v_exp_f32_e32 v68, v68
	s_nop 0
	v_add_f32_e32 v68, 1.0, v68
	v_rcp_f32_e32 v68, v68
	s_nop 0
	v_fma_f32 v68, v68, -2.0, 1.0
	v_cvt_pk_bf16_f32 v68, v68, s0
	ds_write_b16 v214, v68 offset:46080
	ds_read_u16 v68, v219 offset:48896
	ds_read_u16 v69, v219 offset:49536
	ds_read_u16 v70, v219 offset:50176
	s_waitcnt lgkmcnt(2)
	v_lshlrev_b32_e32 v68, 16, v68
	s_waitcnt lgkmcnt(1)
	v_lshlrev_b32_e32 v69, 16, v69
	v_sub_f32_e32 v68, v68, v69
	s_waitcnt lgkmcnt(0)
	v_lshlrev_b32_e32 v70, 16, v70
	v_sub_f32_e32 v70, v70, v69
	v_fmac_f32_e32 v69, v67, v68
	v_fmac_f32_e32 v69, v66, v70
	v_add_f32_e32 v66, v69, v69
	v_mul_f32_e32 v66, 0x3fb8aa3b, v66
	v_exp_f32_e32 v66, v66
	s_nop 0
	v_add_f32_e32 v66, 1.0, v66
	v_rcp_f32_e32 v66, v66
	s_nop 0
	v_fma_f32 v66, v66, -2.0, 1.0
	v_cvt_pk_bf16_f32 v66, v66, s0
	ds_write_b16 v214, v66 offset:46592
	ds_read_u16 v66, v216 offset:49024
	ds_read_u16 v67, v216 offset:49664
	ds_read_u16 v68, v216 offset:50304
	s_waitcnt lgkmcnt(2)
	v_lshlrev_b32_e32 v66, 16, v66
	s_waitcnt lgkmcnt(1)
	v_lshlrev_b32_e32 v67, 16, v67
	v_sub_f32_e32 v66, v66, v67
	s_waitcnt lgkmcnt(0)
	v_lshlrev_b32_e32 v68, 16, v68
	v_sub_f32_e32 v68, v68, v67
	s_waitcnt vmcnt(1)
	v_fmac_f32_e32 v67, v65, v66
	s_waitcnt vmcnt(0)
	v_fmac_f32_e32 v67, v64, v68
	v_cvt_pk_bf16_f32 v66, v67, s0
	ds_write_b16 v214, v66 offset:47104
	ds_read_u16 v66, v217 offset:49024
	ds_read_u16 v67, v217 offset:49664
	ds_read_u16 v68, v217 offset:50304
	s_waitcnt lgkmcnt(2)
	v_lshlrev_b32_e32 v66, 16, v66
	s_waitcnt lgkmcnt(1)
	v_lshlrev_b32_e32 v67, 16, v67
	v_sub_f32_e32 v66, v66, v67
	s_waitcnt lgkmcnt(0)
	v_lshlrev_b32_e32 v68, 16, v68
	v_sub_f32_e32 v68, v68, v67
	v_fmac_f32_e32 v67, v65, v66
	v_fmac_f32_e32 v67, v64, v68
	v_cvt_pk_bf16_f32 v66, v67, s0
	ds_write_b16 v215, v66 offset:45568
	ds_read_u16 v66, v218 offset:49024
	ds_read_u16 v67, v218 offset:49664
	ds_read_u16 v68, v218 offset:50304
	s_waitcnt lgkmcnt(2)
	v_lshlrev_b32_e32 v66, 16, v66
	s_waitcnt lgkmcnt(1)
	v_lshlrev_b32_e32 v67, 16, v67
	v_sub_f32_e32 v66, v66, v67
	s_waitcnt lgkmcnt(0)
	v_lshlrev_b32_e32 v68, 16, v68
	v_sub_f32_e32 v68, v68, v67
	v_fmac_f32_e32 v67, v65, v66
	v_fmac_f32_e32 v67, v64, v68
	v_cvt_pk_bf16_f32 v66, v67, s0
	ds_write_b16 v215, v66 offset:46080
	ds_read_u16 v66, v219 offset:49024
	ds_read_u16 v67, v219 offset:49664
	ds_read_u16 v68, v219 offset:50304
	s_waitcnt lgkmcnt(2)
	v_lshlrev_b32_e32 v66, 16, v66
	s_waitcnt lgkmcnt(1)
	v_lshlrev_b32_e32 v67, 16, v67
	v_sub_f32_e32 v66, v66, v67
	s_waitcnt lgkmcnt(0)
	v_lshlrev_b32_e32 v68, 16, v68
	v_sub_f32_e32 v68, v68, v67
	v_fmac_f32_e32 v67, v65, v66
	v_fmac_f32_e32 v67, v64, v68
	v_cvt_pk_bf16_f32 v64, v67, s0
	ds_write_b16 v215, v64 offset:46592
	v_mov_b32_e32 v64, v228
	s_waitcnt lgkmcnt(0)
	s_barrier
	s_nop 0
	v_ashrrev_i32_e32 v75, 7, v64
	v_bfe_u32 v80, v64, 4, 2
	v_and_b32_e32 v81, 15, v64
	v_bfe_u32 v76, v64, 6, 1
	v_mul_lo_u32 v64, v75, s54
	v_lshl_or_b32 v66, v76, 11, v64
	v_lshl_add_u32 v64, v75, 1, s83
	v_or_b32_e32 v64, v64, v76
	v_ashrrev_i32_e32 v65, 31, v64
	v_lshlrev_b64 v[72:73], 16, v[64:65]
	v_mul_lo_u32 v75, v75, 6
	v_lshlrev_b32_e32 v196, 4, v80
	v_lshl_add_u64 v[72:73], s[20:21], 0, v[72:73]
	v_or_b32_e32 v75, v75, v76
	v_lshlrev_b32_e32 v74, 7, v81
	v_lshl_add_u64 v[72:73], v[72:73], 0, v[196:197]
	v_lshlrev_b32_e32 v82, 12, v75
	v_mov_b32_e32 v75, v197
	v_or3_b32 v68, v66, v74, v196
	v_lshl_add_u64 v[84:85], v[72:73], 0, v[74:75]
	global_load_dwordx4 v[88:91], v[84:85], off
	global_load_dwordx4 v[92:95], v[84:85], off offset:64
	global_load_dwordx4 v[96:99], v[84:85], off offset:2048
	global_load_dwordx4 v[100:103], v[84:85], off offset:2112
	v_lshlrev_b32_e32 v76, 10, v80
	v_lshlrev_b32_e32 v77, 2, v81
	v_or3_b32 v86, v82, v76, v77
	v_add_u32_e32 v82, 0x3000, v86
	v_add_co_u32_e32 v80, vcc, s47, v84
	s_nop 1
	v_addc_co_u32_e32 v81, vcc, 0, v85, vcc
	global_load_dwordx4 v[104:107], v[80:81], off
	global_load_dwordx4 v[108:111], v[80:81], off offset:64
	global_load_dwordx4 v[112:115], v[80:81], off offset:2048
	global_load_dwordx4 v[116:119], v[80:81], off offset:2112
	ds_read_b128 v[64:67], v68 offset:20480
	ds_read_b128 v[68:71], v68 offset:20544
	s_waitcnt vmcnt(6) lgkmcnt(0)
	v_mfma_f32_16x16x32_bf16 v[72:75], v[64:67], v[88:91], 0
	v_mfma_f32_16x16x32_bf16 v[72:75], v[68:71], v[92:95], v[72:75]
	s_waitcnt vmcnt(4)
	v_mfma_f32_16x16x32_bf16 v[76:79], v[64:67], v[96:99], 0
	v_mfma_f32_16x16x32_bf16 v[76:79], v[68:71], v[100:103], v[76:79]
	s_waitcnt vmcnt(2)
	v_mfma_f32_16x16x32_bf16 v[120:123], v[64:67], v[104:107], 0
	v_mfma_f32_16x16x32_bf16 v[120:123], v[68:71], v[108:111], v[120:123]
	s_waitcnt vmcnt(0)
	v_mfma_f32_16x16x32_bf16 v[124:127], v[64:67], v[112:115], 0
	v_mfma_f32_16x16x32_bf16 v[124:127], v[68:71], v[116:119], v[124:127]
	s_nop 7
	s_nop 1
	ds_write2_b32 v82, v72, v76 offset1:16
	ds_write2_b32 v82, v73, v77 offset0:64 offset1:80
	ds_write2_b32 v82, v74, v78 offset0:128 offset1:144
	ds_write2_b32 v82, v75, v79 offset0:192 offset1:208
	ds_write2_b32 v82, v120, v124 offset0:32 offset1:48
	ds_write2_b32 v82, v121, v125 offset0:96 offset1:112
	ds_write2_b32 v82, v122, v126 offset0:160 offset1:176
	ds_write2_b32 v82, v123, v127 offset0:224 offset1:240
	s_waitcnt lgkmcnt(0)
	s_barrier
	ds_read2st64_b32 v[64:65], v161 offset1:16
	v_mov_b32_e32 v68, v197
	s_waitcnt lgkmcnt(0)
	v_mul_f32_e32 v66, v204, v65
	v_mul_f32_e32 v67, v66, v66
	s_nop 1
	v_mov_b32_dpp v68, v67 quad_perm:[1,0,3,2] row_mask:0xf bank_mask:0xf
	v_fmac_f32_e32 v68, v66, v66
	s_nop 1
	v_add_f32_dpp v67, v68, v68 quad_perm:[2,3,0,1] row_mask:0xf bank_mask:0xf bound_ctrl:1
	s_nop 1
	v_add_f32_dpp v67, v67, v67 row_ror:4 row_mask:0xf bank_mask:0xf bound_ctrl:1
	s_nop 1
	v_add_f32_dpp v67, v67, v67 row_ror:8 row_mask:0xf bank_mask:0xf bound_ctrl:1
	s_nop 0
	v_readlane_b32 s3, v67, 16
	v_readlane_b32 s17, v67, 48
	v_readlane_b32 s2, v67, 0
	v_readlane_b32 s16, v67, 32
	v_mov_b32_e32 v67, s3
	v_mov_b32_e32 v68, s17
	v_add_f32_e32 v67, s2, v67
	v_add_f32_e32 v68, s16, v68
	v_add_f32_e32 v67, v67, v68
	v_max_f32_e32 v67, 0x2b8cbccc, v67
	v_rsq_f32_e32 v67, v67
	s_nop 0
	v_mul_f32_e32 v68, v66, v67
	ds_read2st64_b32 v[66:67], v161 offset0:48 offset1:64
	s_waitcnt lgkmcnt(0)
	v_add_f32_e32 v66, v207, v66
	v_max_f32_e64 v69, -v66, 0
	v_mul_f32_e64 v66, |v66|, s71
	v_exp_f32_e32 v66, v66
	v_add_f32_e32 v67, v208, v67
	v_mul_f32_e32 v67, 0xbfb8aa3b, v67
	v_exp_f32_e32 v67, v67
	v_add_f32_e32 v66, 1.0, v66
	v_cmp_gt_f32_e32 vcc, s69, v66
	v_add_f32_e32 v67, 1.0, v67
	s_nop 0
	v_cndmask_b32_e64 v70, 0, 32, vcc
	v_ldexp_f32 v66, v66, v70
	v_log_f32_e32 v66, v66
	v_rcp_f32_e32 v67, v67
	v_mul_f32_e32 v70, 0x3f317217, v66
	v_fma_f32 v70, v66, s38, -v70
	v_fmac_f32_e32 v70, 0x3377d1cf, v66
	v_fmac_f32_e32 v70, 0x3f317217, v66
	v_cmp_lt_f32_e64 s[16:17], |v66|, s39
	s_nop 1
	v_cndmask_b32_e64 v66, v66, v70, s[16:17]
	v_cndmask_b32_e32 v70, 0, v237, vcc
	v_sub_f32_e32 v66, v66, v70
	v_add_f32_e32 v66, v69, v66
	v_add_f32_e32 v69, -1.0, v67
	v_sub_f32_e32 v66, -0.5, v66
	v_fma_f32 v69, v205, v69, 1.0
	v_mul_f32_e32 v66, 0x3fb8aa3b, v66
	v_mul_f32_e32 v65, v65, v69
	v_exp_f32_e32 v66, v66
	v_mul_f32_e32 v64, v64, v65
	v_mul_f32_e32 v69, v206, v64
	v_mov_b32_e32 v70, v197
	v_mul_f32_e32 v66, 0xbfb8aa3b, v66
	v_exp_f32_e32 v66, v66
	v_mov_b32_dpp v70, v69 quad_perm:[1,0,3,2] row_mask:0xf bank_mask:0xf
	v_fmac_f32_e32 v70, v206, v64
	s_nop 1
	v_add_f32_dpp v64, v70, v70 quad_perm:[2,3,0,1] row_mask:0xf bank_mask:0xf bound_ctrl:1
	s_nop 1
	v_add_f32_dpp v64, v64, v64 row_ror:4 row_mask:0xf bank_mask:0xf bound_ctrl:1
	s_nop 1
	v_add_f32_dpp v64, v64, v64 row_ror:8 row_mask:0xf bank_mask:0xf bound_ctrl:1
	s_nop 0
	v_readlane_b32 s16, v64, 0
	v_readlane_b32 s2, v64, 16
	v_readlane_b32 s17, v64, 32
	v_readlane_b32 s3, v64, 48
	v_mul_f32_e32 v64, v68, v67
	ds_write2st64_b32 v161, v64, v68 offset0:64 offset1:80
	ds_write2st64_b32 v161, v65, v66 offset0:16 offset1:48
	s_and_saveexec_b64 s[22:23], s[12:13]
	s_cbranch_execz .LBB0_520
	v_or_b32_e32 v64, s34, v187
	v_sub_u32_e32 v65, s35, v187
	v_cndmask_b32_e64 v64, v65, v64, s[14:15]
	v_lshl_add_u32 v64, v64, 4, v189
	v_mov_b32_e32 v66, s2
	v_mov_b32_e32 v67, s3
	v_ashrrev_i32_e32 v65, 31, v64
	v_pk_add_f32 v[66:67], s[16:17], v[66:67]
	v_lshl_add_u64 v[64:65], v[64:65], 2, s[94:95]
	v_add_f32_e32 v66, v66, v67
	global_store_dword v[64:65], v66, off

	.amdhsa_kernel _Z14fwd_megakernel1P
		.amdhsa_group_segment_fixed_size 61456
		.amdhsa_private_segment_fixed_size 0
		.amdhsa_kernarg_size 560
		.amdhsa_user_sgpr_count 2
		.amdhsa_user_sgpr_dispatch_ptr 0
		.amdhsa_user_sgpr_queue_ptr 0
		.amdhsa_user_sgpr_kernarg_segment_ptr 1
		.amdhsa_user_sgpr_dispatch_id 0
		.amdhsa_user_sgpr_kernarg_preload_length 0
		.amdhsa_user_sgpr_kernarg_preload_offset 0
		.amdhsa_user_sgpr_private_segment_size 0
		.amdhsa_uses_dynamic_stack 0
		.amdhsa_enable_private_segment 0
		.amdhsa_system_sgpr_workgroup_id_x 1
		.amdhsa_system_sgpr_workgroup_id_y 0
		.amdhsa_system_sgpr_workgroup_id_z 0
		.amdhsa_system_sgpr_workgroup_info 0
		.amdhsa_system_vgpr_workitem_id 2
		.amdhsa_next_free_vgpr 256
		.amdhsa_next_free_sgpr 102
		.amdhsa_accum_offset 256
		.amdhsa_reserve_vcc 1
		.amdhsa_float_round_mode_32 0
		.amdhsa_float_round_mode_16_64 0
		.amdhsa_float_denorm_mode_32 3
		.amdhsa_float_denorm_mode_16_64 3
		.amdhsa_dx10_clamp 1
		.amdhsa_ieee_mode 1
		.amdhsa_fp16_overflow 0
		.amdhsa_tg_split 0
		.amdhsa_exception_fp_ieee_invalid_op 0
		.amdhsa_exception_fp_denorm_src 0
		.amdhsa_exception_fp_ieee_div_zero 0
		.amdhsa_exception_fp_ieee_overflow 0
		.amdhsa_exception_fp_ieee_underflow 0
		.amdhsa_exception_fp_ieee_inexact 0
		.amdhsa_exception_int_div_zero 0
	.end_amdhsa_kernel

amdhsa.kernels:
  - .agpr_count:     0
    .args:
      - .offset:         0
        .size:           304
        .value_kind:     by_value
      - .offset:         304
        .size:           4
        .value_kind:     hidden_block_count_x
      - .offset:         308
        .size:           4
        .value_kind:     hidden_block_count_y
      - .offset:         312
        .size:           4
        .value_kind:     hidden_block_count_z
      - .offset:         316
        .size:           2
        .value_kind:     hidden_group_size_x
      - .offset:         318
        .size:           2
        .value_kind:     hidden_group_size_y
      - .offset:         320
        .size:           2
        .value_kind:     hidden_group_size_z
      - .offset:         322
        .size:           2
        .value_kind:     hidden_remainder_x
      - .offset:         324
        .size:           2
        .value_kind:     hidden_remainder_y
      - .offset:         326
        .size:           2
        .value_kind:     hidden_remainder_z
      - .offset:         344
        .size:           8
        .value_kind:     hidden_global_offset_x
      - .offset:         352
        .size:           8
        .value_kind:     hidden_global_offset_y
      - .offset:         360
        .size:           8
        .value_kind:     hidden_global_offset_z
      - .offset:         368
        .size:           2
        .value_kind:     hidden_grid_dims
      - .offset:         392
        .size:           8
        .value_kind:     hidden_multigrid_sync_arg
    .group_segment_fixed_size: 61456
    .kernarg_segment_align: 8
    .kernarg_segment_size: 560
    .language:       OpenCL C
    .language_version:
      - 2
      - 0
    .max_flat_workgroup_size: 256
    .name:           _Z14fwd_megakernel1P
    .private_segment_fixed_size: 0
    .sgpr_count:     108
    .sgpr_spill_count: 204
    .symbol:         _Z14fwd_megakernel1P.kd
    .uniform_work_group_size: 1
    .uses_dynamic_stack: false
    .vgpr_count:     256
    .vgpr_spill_count: 0
    .wavefront_size: 64
